# latency de-serialisation: OCB gate loads issued together, compress slab loads unrolled (5 loads in flight), nsaw/swa prologues issue the first K/V DMAs before the bias-table loads and wait once
# speedup vs baseline: 1.0144x; 1.0055x over previous
.LBB0_241:
	s_cmp_gt_i32 s4, 1
	s_mov_b64 s[20:21], -1
	s_cbranch_scc0 .LBB0_265
	s_lshl_b32 s18, s81, 4
	s_bfe_u32 s14, s81, 0x10007
	s_and_b32 s22, s18, 0xfffff000
	s_lshl_b32 s5, s81, 5
	s_lshl_b32 s16, s14, 3
	s_ashr_i32 s23, s22, 31
	s_and_b32 s5, s5, 0xfe0
	s_add_i32 s70, s16, s0
	s_lshl_b64 s[18:19], s[22:23], 13
	s_add_u32 s42, s1, s18
	v_or_b32_e32 v144, s5, v210
	s_addc_u32 s43, s2, s19
	s_lshl_b32 s20, s70, 6
	v_lshlrev_b32_e32 v0, 13, v144
	s_ashr_i32 s21, s20, 31
	v_lshl_add_u64 v[2:3], s[42:43], 0, v[0:1]
	v_lshlrev_b32_e32 v0, 1, v124
	v_lshl_add_u64 v[2:3], s[20:21], 1, v[2:3]
	v_lshl_add_u64 v[10:11], v[2:3], 0, v[0:1]
	s_mov_b64 s[18:19], 0x1400
	v_add_co_u32_e32 v2, vcc, s83, v10
	v_lshl_add_u64 v[6:7], v[10:11], 0, s[18:19]
	s_nop 0
	v_addc_co_u32_e32 v3, vcc, 0, v11, vcc
	s_mov_b64 s[18:19], 0x21400
	v_lshl_add_u64 v[14:15], v[10:11], 0, s[18:19]
	v_add_co_u32_e32 v10, vcc, 0x21000, v10
	global_load_dwordx4 v[2:5], v[2:3], off offset:1024
	s_nop 0
	global_load_dwordx4 v[6:9], v[6:7], off offset:64
	v_addc_co_u32_e32 v11, vcc, 0, v11, vcc
	global_load_dwordx4 v[10:13], v[10:11], off offset:1024
	s_nop 0
	global_load_dwordx4 v[14:17], v[14:15], off offset:64
	v_sub_u32_e64 v0, s5, v208 clamp
	s_nop 0
	v_readfirstlane_b32 s18, v0
	s_barrier
	s_mov_b32 s100, s16
	s_lshl_b32 s14, s14, 7
	s_add_u32 s14, s42, s14
	s_addc_u32 s16, s43, 0
	s_add_u32 s42, s14, 0x1c00
	s_load_dwordx2 s[72:73], s[6:7], 0x60
	s_addc_u32 s43, s16, 0
	s_add_u32 s44, s14, 0x1d00
	s_addc_u32 s45, s16, 0
	s_lshr_b32 s14, s18, 6
	s_lshr_b32 s19, s5, 6
	s_sub_i32 s18, s19, s14
	s_cmp_lt_i32 s18, 0
	s_cbranch_scc1 .Lswa_nodma
	v_lshlrev_b64 v[18:19], 1, v[126:127]
	v_lshl_add_u64 v[20:21], s[42:43], 0, v[18:19]
	s_lshl_b32 s16, s14, 19
	v_lshl_add_u64 v[18:19], s[44:45], 0, v[18:19]
	s_add_i32 m0, s79, 0x8000
	s_add_i32 s23, s79, 0xa000
	v_lshl_add_u64 v[22:23], v[20:21], 0, s[16:17]
	global_load_lds_dwordx4 v[22:23], off
	v_lshl_add_u64 v[22:23], v[18:19], 0, s[16:17]
	s_mov_b32 m0, s23
	s_cmp_lg_u32 s19, s14
	global_load_lds_dwordx4 v[22:23], off
	s_cbranch_scc0 .Lswa_nodma
	s_lshl_b32 s16, s14, 18
	s_lshl_b32 s16, s16, 1
	s_add_i32 s16, s16, 0x80000
	v_lshl_add_u64 v[20:21], v[20:21], 0, s[16:17]
	s_add_i32 m0, s79, 0xc000
	v_lshl_add_u64 v[18:19], v[18:19], 0, s[16:17]
	global_load_lds_dwordx4 v[20:21], off
	s_add_i32 m0, s79, 0xe000
	s_nop 0
	global_load_lds_dwordx4 v[18:19], off
.Lswa_nodma:
	s_and_saveexec_b64 s[98:99], s[38:39]
	s_cbranch_execz .LBB0_244
	v_add_lshl_u32 v18, v211, s100, 10
	v_ashrrev_i32_e32 v19, 31, v18
	v_lshl_add_u64 v[18:19], v[18:19], 2, v[138:139]
	global_load_dwordx4 v[18:21], v[18:19], off offset:3584
	s_waitcnt vmcnt(0)
	ds_write_b128 v212, v[18:21]
.LBB0_244:
	s_or_b64 exec, exec, s[98:99]
	s_waitcnt vmcnt(0)

.LBB0_265:
	s_and_b64 vcc, exec, s[20:21]
	s_cbranch_vccz .LBB0_232
	s_cmp_lg_u32 s4, 1
	s_mov_b64 s[20:21], -1
	s_cbranch_scc0 .LBB0_275
	s_cmpk_lt_u32 s81, 0x80
	s_cselect_b64 s[20:21], -1, 0
	s_bfe_u32 s4, s81, 0x30004
	s_and_b32 s5, s81, 15
	s_barrier
	s_and_saveexec_b64 s[22:23], s[40:41]
	s_cbranch_execz .LBB0_270
	s_and_b32 s16, s81, 0x7f
	s_and_b64 s[18:19], s[20:21], exec
	s_movk_i32 s14, 0x800
	s_cselect_b32 s18, s14, 0xa00
	s_lshl_b32 s16, s16, 19
	s_lshl_b32 s14, s5, 8
	s_and_b32 s16, s16, 0x2000000
	s_add_u32 s16, s1, s16
	s_addc_u32 s19, s2, 0
	s_add_u32 s16, s16, s18
	s_addc_u32 s18, s19, 0
	s_lshl_b32 s19, s4, 7
	s_and_b32 s19, s19, 0x180
	s_add_u32 s42, s16, s19
	s_addc_u32 s43, s18, 0
	s_mov_b64 s[44:45], 0
	v_mov_b32_e32 v2, v218
	v_mov_b32_e32 v3, v122
	v_and_b32_e32 v56, 56, v218
	v_lshlrev_b32_e32 v56, 1, v56
	v_mov_b32_e32 v57, v1
	s_mov_b64 s[18:19], exec
	s_movk_i32 s16, 0x80
	v_cmp_gt_u32_e64 s[44:45], s16, v122
	s_nop 1
	s_and_b64 exec, exec, s[44:45]
	v_add_u32_e32 v53, 2048, v122
	v_ashrrev_i32_e32 v54, 3, v53
	v_add_u32_e32 v46, s14, v54
	v_min_i32_e32 v46, 0xfff, v46
	v_ashrrev_i32_e32 v47, 31, v46
	v_lshlrev_b64 v[46:47], 13, v[46:47]
	v_lshl_add_u64 v[46:47], s[42:43], 0, v[46:47]
	v_lshl_add_u64 v[46:47], v[46:47], 0, v[56:57]
	global_load_dwordx4 v[34:37], v[46:47], off
	v_lshlrev_b32_e32 v52, 7, v54
	v_lshrrev_b32_e32 v54, 7, v53
	v_xor_b32_e32 v54, v54, v53
	v_lshlrev_b32_e32 v54, 4, v54
	v_and_b32_e32 v54, 0x70, v54
	v_add3_u32 v52, 0, v52, v54
	s_mov_b64 exec, s[18:19]
	v_mov_b32_e32 v53, v122
	v_ashrrev_i32_e32 v54, 3, v53
	v_add_u32_e32 v38, s14, v54
	v_min_i32_e32 v38, 0xfff, v38
	v_ashrrev_i32_e32 v39, 31, v38
	v_lshlrev_b64 v[38:39], 13, v[38:39]
	v_lshl_add_u64 v[38:39], s[42:43], 0, v[38:39]
	v_lshl_add_u64 v[38:39], v[38:39], 0, v[56:57]
	global_load_dwordx4 v[18:21], v[38:39], off
	v_lshlrev_b32_e32 v48, 7, v54
	v_lshrrev_b32_e32 v54, 7, v53
	v_xor_b32_e32 v54, v54, v53
	v_lshlrev_b32_e32 v54, 4, v54
	v_and_b32_e32 v54, 0x70, v54
	v_add3_u32 v48, 0, v48, v54
	v_add_u32_e32 v53, 512, v122
	v_ashrrev_i32_e32 v54, 3, v53
	v_add_u32_e32 v40, s14, v54
	v_min_i32_e32 v40, 0xfff, v40
	v_ashrrev_i32_e32 v41, 31, v40
	v_lshlrev_b64 v[40:41], 13, v[40:41]
	v_lshl_add_u64 v[40:41], s[42:43], 0, v[40:41]
	v_lshl_add_u64 v[40:41], v[40:41], 0, v[56:57]
	global_load_dwordx4 v[22:25], v[40:41], off
	v_lshlrev_b32_e32 v49, 7, v54
	v_lshrrev_b32_e32 v54, 7, v53
	v_xor_b32_e32 v54, v54, v53
	v_lshlrev_b32_e32 v54, 4, v54
	v_and_b32_e32 v54, 0x70, v54
	v_add3_u32 v49, 0, v49, v54
	v_add_u32_e32 v53, 1024, v122
	v_ashrrev_i32_e32 v54, 3, v53
	v_add_u32_e32 v42, s14, v54
	v_min_i32_e32 v42, 0xfff, v42
	v_ashrrev_i32_e32 v43, 31, v42
	v_lshlrev_b64 v[42:43], 13, v[42:43]
	v_lshl_add_u64 v[42:43], s[42:43], 0, v[42:43]
	v_lshl_add_u64 v[42:43], v[42:43], 0, v[56:57]
	global_load_dwordx4 v[26:29], v[42:43], off
	v_lshlrev_b32_e32 v50, 7, v54
	v_lshrrev_b32_e32 v54, 7, v53
	v_xor_b32_e32 v54, v54, v53
	v_lshlrev_b32_e32 v54, 4, v54
	v_and_b32_e32 v54, 0x70, v54
	v_add3_u32 v50, 0, v50, v54
	v_add_u32_e32 v53, 1536, v122
	v_ashrrev_i32_e32 v54, 3, v53
	v_add_u32_e32 v44, s14, v54
	v_min_i32_e32 v44, 0xfff, v44
	v_ashrrev_i32_e32 v45, 31, v44
	v_lshlrev_b64 v[44:45], 13, v[44:45]
	v_lshl_add_u64 v[44:45], s[42:43], 0, v[44:45]
	v_lshl_add_u64 v[44:45], v[44:45], 0, v[56:57]
	global_load_dwordx4 v[30:33], v[44:45], off
	v_lshlrev_b32_e32 v51, 7, v54
	v_lshrrev_b32_e32 v54, 7, v53
	v_xor_b32_e32 v54, v54, v53
	v_lshlrev_b32_e32 v54, 4, v54
	v_and_b32_e32 v54, 0x70, v54
	v_add3_u32 v51, 0, v51, v54
	s_waitcnt vmcnt(4)
	s_and_b64 exec, exec, s[44:45]
	ds_write_b128 v52, v[34:37]
	s_mov_b64 exec, s[18:19]
	s_waitcnt vmcnt(3)
	ds_write_b128 v48, v[18:21]
	s_waitcnt vmcnt(2)
	ds_write_b128 v49, v[22:25]
	s_waitcnt vmcnt(1)
	ds_write_b128 v50, v[26:29]
	s_waitcnt vmcnt(0)
	ds_write_b128 v51, v[30:33]

.LBB0_275:
	s_and_b64 vcc, exec, s[20:21]
	s_cbranch_vccz .LBB0_232
	s_lshl_b32 s16, s81, 4
	s_lshl_b32 s4, s81, 6
	s_and_b32 s20, s16, 0xfffff000
	s_and_b32 s5, s4, 0xfc0
	s_ashr_i32 s21, s20, 31
	s_bfe_u32 s14, s81, 0x20006
	s_add_i32 s4, s5, s33
	s_lshl_b64 s[18:19], s[20:21], 13
	s_add_u32 s16, s1, s18
	v_mov_b32_e32 v0, 0x1ff
	s_addc_u32 s21, s2, s19
	v_sub_u32_e64 v0, s5, v0 clamp
	s_lshl_b32 s18, s14, 8
	v_readfirstlane_b32 s5, v0
	s_or_b32 s18, s18, s37
	s_lshr_b32 s5, s5, 6
	s_lshl_b32 s22, s18, 1
	s_add_u32 s18, s16, s22
	s_addc_u32 s19, s21, 0
	v_lshlrev_b32_e32 v0, 1, v124
	v_lshl_add_u64 v[10:11], s[18:19], 0, v[0:1]
	s_lshl_b32 s18, s14, 7
	s_add_u32 s16, s16, s18
	s_addc_u32 s18, s21, 0
	v_or_b32_e32 v144, s4, v210
	s_add_u32 s42, s16, 0x1000
	v_or_b32_e32 v158, 16, v144
	s_addc_u32 s43, s18, 0
	v_ashrrev_i32_e32 v145, 31, v144
	v_ashrrev_i32_e32 v159, 31, v158
	s_add_u32 s44, s16, 0x1200
	v_lshlrev_b64 v[2:3], 13, v[144:145]
	v_lshlrev_b64 v[12:13], 13, v[158:159]
	s_addc_u32 s45, s18, 0
	s_lshl_b32 s16, s14, 14
	v_lshl_add_u64 v[6:7], v[10:11], 0, v[2:3]
	v_lshl_add_u64 v[14:15], v[10:11], 0, v[12:13]
	v_lshl_add_u64 v[22:23], v[140:141], 0, s[16:17]
	global_load_dwordx4 v[2:5], v[6:7], off
	s_nop 0
	global_load_dwordx4 v[6:9], v[6:7], off offset:64
	s_nop 0
	global_load_dwordx4 v[10:13], v[14:15], off
	s_nop 0
	global_load_dwordx4 v[14:17], v[14:15], off offset:64
	s_barrier
	s_and_b32 s18, s81, 63
	s_sub_i32 s14, s18, s5
	v_lshlrev_b64 v[18:19], 1, v[126:127]
	v_lshl_add_u64 v[162:163], s[42:43], 0, v[18:19]
	v_lshl_add_u64 v[164:165], s[44:45], 0, v[18:19]
	s_cmp_lt_i32 s14, 0
	s_cbranch_scc1 .Lnsaw_nodma
	s_lshl_b32 s16, s5, 19
	s_add_i32 m0, s79, 0x8000
	s_add_i32 s19, s79, 0xa000
	v_lshl_add_u64 v[18:19], v[162:163], 0, s[16:17]
	global_load_lds_dwordx4 v[18:19], off
	v_lshl_add_u64 v[18:19], v[164:165], 0, s[16:17]
	s_mov_b32 m0, s19
	s_cmp_lg_u32 s18, s5
	global_load_lds_dwordx4 v[18:19], off
	s_cbranch_scc0 .Lnsaw_nodma
	s_lshl_b32 s16, s5, 18
	s_lshl_b32 s16, s16, 1
	s_add_i32 s16, s16, 0x80000
	v_lshl_add_u64 v[18:19], v[162:163], 0, s[16:17]
	s_add_i32 m0, s79, 0xc000
	s_nop 0
	global_load_lds_dwordx4 v[18:19], off
	v_lshl_add_u64 v[18:19], v[164:165], 0, s[16:17]
	s_add_i32 m0, s79, 0xe000
	s_nop 0
	global_load_lds_dwordx4 v[18:19], off
.Lnsaw_nodma:
	global_load_dwordx4 v[18:21], v[22:23], off
	v_add_co_u32_e32 v24, vcc, 0x2000, v22
	s_nop 1
	v_addc_co_u32_e32 v25, vcc, 0, v23, vcc
	global_load_dwordx4 v[26:29], v[24:25], off
	s_waitcnt vmcnt(1)
	ds_write_b128 v212, v[18:21]
	s_waitcnt vmcnt(0)
	ds_write_b128 v212, v[26:29] offset:8192
	s_waitcnt vmcnt(0)

.LBB0_364:
	v_and_b32_e32 v20, 64, v147
	s_lshl_b32 s4, s25, 3
	v_readlane_b32 s5, v255, 21
	v_xor_b32_e32 v0, 16, v147
	v_add_u32_e32 v38, 64, v20
	s_add_i32 s4, s4, s5
	v_cmp_lt_i32_e32 vcc, v0, v38
	s_ashr_i32 s5, s4, 31
	s_lshl_b64 s[4:5], s[4:5], 13
	v_cndmask_b32_e32 v0, v147, v0, vcc
	v_lshlrev_b32_e32 v119, 2, v0
	v_xor_b32_e32 v0, 32, v147
	v_lshl_add_u64 v[116:117], v[124:125], 0, s[4:5]
	v_cmp_lt_i32_e32 vcc, v0, v38
	s_add_i32 s5, s2, s22
	v_or_b32_e32 v114, s5, v122
	v_cndmask_b32_e32 v0, v147, v0, vcc
	v_mul_u32_u24_e32 v118, 3, v145
	v_readlane_b32 s6, v255, 18
	v_lshlrev_b32_e32 v137, 2, v0
	v_lshlrev_b32_e32 v0, 1, v118
	v_readlane_b32 s7, v255, 19
	v_ashrrev_i32_e32 v115, 31, v114
	v_lshlrev_b64 v[120:121], 13, v[114:115]
	v_lshl_add_u64 v[18:19], s[6:7], 0, v[0:1]
	v_lshl_add_u64 v[24:25], v[18:19], 0, v[120:121]
	s_movk_i32 s5, 0x1000
	v_add_co_u32_e32 v24, vcc, s5, v24
	ds_bpermute_b32 v22, v119, v188
	s_nop 0
	v_addc_co_u32_e32 v25, vcc, 0, v25, vcc
	global_load_ushort v0, v[24:25], off offset:3584
	s_mov_b64 s[98:99], 0x8000
	v_lshl_add_u64 v[56:57], v[24:25], 0, s[98:99]
	global_load_ushort v58, v[56:57], off offset:3584
	s_mov_b32 s4, 0
	s_movk_i32 s83, 0x1000
	v_sub_u32_e32 v40, v225, v143
	v_add_u32_e32 v41, s14, v228
	v_mov_b32_e32 v42, v227
	v_mov_b32_e32 v43, v223
	v_mov_b32_e32 v44, v222
	v_mov_b32_e32 v45, v226
	v_mov_b32_e32 v31, 0
	s_waitcnt vmcnt(0)
	v_lshlrev_b32_e32 v0, 16, v0
	v_mul_f32_e32 v0, 0xbfb8aa3b, v0
	v_exp_f32_e32 v0, v0
	s_nop 0
	v_add_f32_e32 v0, 1.0, v0
	v_div_scale_f32 v21, s[6:7], v0, v0, 1.0
	v_rcp_f32_e32 v23, v21
	s_nop 0
	v_fma_f32 v24, -v21, v23, 1.0
	v_fmac_f32_e32 v23, v24, v23
	v_div_scale_f32 v24, vcc, 1.0, v0, 1.0
	v_mul_f32_e32 v25, v24, v23
	v_fma_f32 v26, -v21, v25, v24
	v_fmac_f32_e32 v25, v26, v23
	v_fma_f32 v21, -v21, v25, v24
	v_div_fmas_f32 v21, v21, v23, v25
	ds_bpermute_b32 v23, v119, v189
	v_div_fixup_f32 v0, v21, v0, 1.0
	s_waitcnt lgkmcnt(0)
	v_pk_add_f32 v[22:23], v[188:189], v[22:23]
	ds_bpermute_b32 v24, v137, v22
	ds_bpermute_b32 v25, v137, v23
	s_waitcnt lgkmcnt(0)
	v_pk_add_f32 v[28:29], v[22:23], v[24:25]
	s_nop 0
	v_div_scale_f32 v21, s[6:7], v28, v28, 1.0
	v_rcp_f32_e32 v22, v21
	v_cmp_lt_f32_e64 s[42:43], 0, v29
	v_fma_f32 v23, -v21, v22, 1.0
	v_fmac_f32_e32 v22, v23, v22
	v_div_scale_f32 v23, vcc, 1.0, v28, 1.0
	v_mul_f32_e32 v24, v23, v22
	v_fma_f32 v25, -v21, v24, v23
	v_fmac_f32_e32 v24, v25, v22
	v_fma_f32 v21, -v21, v24, v23
	v_div_fmas_f32 v21, v21, v22, v24
	v_div_fixup_f32 v21, v21, v28, 1.0
	v_cmp_lt_f32_e32 vcc, 0, v28
	v_mov_b32_e32 v23, 0
	s_nop 0
	v_cndmask_b32_e32 v34, 0, v21, vcc
	v_mul_f32_e32 v0, v34, v0
	v_pk_mul_f32 v[26:27], v[100:101], v[0:1] op_sel_hi:[1,0]
	v_pk_mul_f32 v[24:25], v[98:99], v[0:1] op_sel_hi:[1,0]
	global_store_dwordx4 v[116:117], v[24:27], off
	v_mov_b32_e32 v35, v34
	s_nop 0
	v_pk_mul_f32 v[26:27], v[104:105], v[0:1] op_sel_hi:[1,0]
	v_pk_mul_f32 v[24:25], v[102:103], v[0:1] op_sel_hi:[1,0]
	global_store_dwordx4 v[116:117], v[24:27], off offset:1024
	v_or_b32_e32 v102, 4, v114
	v_ashrrev_i32_e32 v103, 31, v102
	v_pk_mul_f32 v[26:27], v[108:109], v[0:1] op_sel_hi:[1,0]
	v_pk_mul_f32 v[24:25], v[106:107], v[0:1] op_sel_hi:[1,0]
	global_store_dwordx4 v[116:117], v[24:27], off offset:2048
	s_nop 1
	v_pk_mul_f32 v[26:27], v[112:113], v[0:1] op_sel_hi:[1,0]
	v_pk_mul_f32 v[24:25], v[110:111], v[0:1] op_sel_hi:[1,0]
	v_div_scale_f32 v0, s[6:7], v29, v29, 1.0
	v_rcp_f32_e32 v21, v0
	global_store_dwordx4 v[116:117], v[24:27], off offset:3072
	v_lshlrev_b64 v[112:113], 13, v[102:103]
	v_lshl_add_u64 v[18:19], v[18:19], 0, v[112:113]
	v_fma_f32 v22, -v0, v21, 1.0
	v_fmac_f32_e32 v21, v22, v21
	v_div_scale_f32 v22, vcc, 1.0, v29, 1.0
	v_mul_f32_e32 v24, v22, v21
	v_fma_f32 v25, -v0, v24, v22
	v_fmac_f32_e32 v24, v25, v21
	v_fma_f32 v0, -v0, v24, v22
	v_div_fmas_f32 v0, v0, v21, v24
	v_add_co_u32_e32 v18, vcc, s5, v18
	v_div_fixup_f32 v0, v0, v29, 1.0
	s_nop 0
	v_addc_co_u32_e32 v19, vcc, 0, v19, vcc
	v_cndmask_b32_e64 v36, 0, v0, s[42:43]
	v_mov_b32_e32 v0, v58
	v_mov_b32_e32 v37, v36
	v_lshlrev_b32_e32 v0, 16, v0
	v_mul_f32_e32 v0, 0xbfb8aa3b, v0
	v_exp_f32_e32 v0, v0
	s_nop 0
	v_add_f32_e32 v0, 1.0, v0
	v_div_scale_f32 v18, s[6:7], v0, v0, 1.0
	v_rcp_f32_e32 v19, v18
	s_mov_b64 s[6:7], 0x1000
	v_lshl_add_u64 v[110:111], v[116:117], 0, s[6:7]
	s_mov_b64 s[6:7], 0x1400
	v_fma_f32 v21, -v18, v19, 1.0
	v_fmac_f32_e32 v19, v21, v19
	v_div_scale_f32 v21, vcc, 1.0, v0, 1.0
	v_mul_f32_e32 v22, v21, v19
	v_fma_f32 v24, -v18, v22, v21
	v_fmac_f32_e32 v22, v24, v19
	v_fma_f32 v18, -v18, v22, v21
	v_div_fmas_f32 v18, v18, v19, v22
	v_div_fixup_f32 v0, v18, v0, 1.0
	v_mul_f32_e32 v0, v36, v0
	v_add_co_u32_e32 v18, vcc, s5, v116
	v_pk_mul_f32 v[26:27], v[84:85], v[0:1] op_sel_hi:[1,0]
	v_pk_mul_f32 v[24:25], v[82:83], v[0:1] op_sel_hi:[1,0]
	v_addc_co_u32_e32 v19, vcc, 0, v117, vcc
	global_store_dwordx4 v[18:19], v[24:27], off
	v_lshl_add_u64 v[106:107], v[116:117], 0, s[6:7]
	s_mov_b64 s[6:7], 0x1800
	v_pk_mul_f32 v[26:27], v[88:89], v[0:1] op_sel_hi:[1,0]
	v_pk_mul_f32 v[24:25], v[86:87], v[0:1] op_sel_hi:[1,0]
	global_store_dwordx4 v[18:19], v[24:27], off offset:1024
	v_lshl_add_u64 v[108:109], v[116:117], 0, s[6:7]
	s_mov_b64 s[6:7], 0x1c00
	v_pk_mul_f32 v[26:27], v[92:93], v[0:1] op_sel_hi:[1,0]
	v_pk_mul_f32 v[24:25], v[90:91], v[0:1] op_sel_hi:[1,0]
	global_store_dwordx4 v[18:19], v[24:27], off offset:2048
	v_lshl_add_u64 v[104:105], v[116:117], 0, s[6:7]
	s_lshl_b32 s6, s0, 8
	v_pk_mul_f32 v[26:27], v[96:97], v[0:1] op_sel_hi:[1,0]
	v_pk_mul_f32 v[24:25], v[94:95], v[0:1] op_sel_hi:[1,0]
	v_or_b32_e32 v0, v20, v210
	v_lshlrev_b32_e32 v0, 2, v0
	s_add_i32 s5, s2, 0xfffffbe8
	v_subrev_u32_e32 v39, s6, v224
	global_store_dwordx4 v[18:19], v[24:27], off offset:3072
	s_barrier
	s_branch .LBB0_366
